# attention: SIMD-balanced wave to row-group remap (w' = w ^ 3*(w>>2)) so both waves of a SIMD have 5+5 key steps in the neighbour key blocks instead of 6+4
# speedup vs baseline: 1.0025x; 1.0025x over previous
; #define LAS __attribute__((address_space(3)))
; __device__ __forceinline__ void attn_phase(const Params& p, LAS unsigned char* lds, int li, int tid, int G, bf16_t* __restrict__ dst, const bf16_t* __restrict__ ZGA) {
;     asm volatile("" : "+v"(tid));
;     unsigned char* ws = p.ws;
;     const int w = __builtin_amdgcn_readfirstlane(tid >> 6);
.LBB0_294:
	s_or_b64 exec, exec, s[10:11]
	s_mov_b64 s[4:5], s[74:75]
	s_barrier
	s_load_dwordx2 s[6:7], s[4:5], 0x90
	s_and_b32 s1, s3, 7
	s_cmp_lg_u32 s1, 0
	s_cselect_b64 s[8:9], -1, 0
	v_bfe_u32 v1, v254, 8, 1
	v_mul_u32_u24_e32 v1, 0xc0, v1
	v_xor_b32_e32 v0, v254, v1
	v_writelane_b32 v255, s8, 5
	s_cmp_eq_u32 s1, 0
	v_readfirstlane_b32 s0, v0
	v_writelane_b32 v255, s9, 6
	s_mov_b32 s14, 0
	s_cbranch_scc1 .LBB0_298
	s_cmpk_gt_i32 s33, 0x3ff
	s_cbranch_scc1 .LBB0_297
	s_abs_i32 s1, s3
	v_cvt_f32_u32_e32 v1, s1
	s_sub_i32 s2, s3, s33
	s_add_i32 s8, s2, 0x3ff
	s_sub_i32 s2, 0xfffffc01, s2
	v_rcp_iflag_f32_e32 v1, v1
	s_xor_b32 s10, s8, s3
	s_sub_i32 s9, 0, s1
	s_max_i32 s2, s8, s2
	v_mul_f32_e32 v1, 0x4f7ffffe, v1
	v_cvt_u32_f32_e32 v1, v1
	s_ashr_i32 s8, s10, 31
	v_readfirstlane_b32 s10, v1
	s_mul_i32 s9, s9, s10
	s_mul_hi_u32 s9, s10, s9
	s_add_i32 s10, s10, s9
	s_mul_hi_u32 s9, s2, s10
	s_mul_i32 s10, s9, s1
	s_sub_i32 s2, s2, s10
	s_add_i32 s11, s9, 1
	s_sub_i32 s10, s2, s1
	s_cmp_ge_u32 s2, s1
	s_cselect_b32 s9, s11, s9
	s_cselect_b32 s2, s10, s2
	s_add_i32 s10, s9, 1
	s_cmp_ge_u32 s2, s1
	s_cselect_b32 s1, s10, s9
	s_xor_b32 s1, s1, s8
	s_sub_i32 s14, s1, s8

; #define LAS __attribute__((address_space(3)))
; __device__ __forceinline__ void attn_phase(const Params& p, LAS unsigned char* lds, int li, int tid, int G, bf16_t* __restrict__ dst, const bf16_t* __restrict__ ZGA) {
;     asm volatile("" : "+v"(tid));
;     unsigned char* ws = p.ws;
;     const int w = __builtin_amdgcn_readfirstlane(tid >> 6);
.LBB0_1048:
	s_or_b64 exec, exec, s[18:19]
	s_mov_b64 s[8:9], s[92:93]
	s_barrier
	s_load_dwordx2 s[10:11], s[8:9], 0x90
	v_readlane_b32 s0, v255, 5
	v_bfe_u32 v1, v254, 8, 1
	v_mul_u32_u24_e32 v1, 0xc0, v1
	v_xor_b32_e32 v0, v254, v1
	v_readlane_b32 s1, v255, 6
	s_andn2_b64 vcc, exec, s[0:1]
	v_readfirstlane_b32 s0, v0
	s_cbranch_vccnz .LBB0_1052
	v_readlane_b32 s4, v255, 24
	v_readlane_b32 s5, v255, 25
	s_and_b64 vcc, exec, s[4:5]
	s_mov_b32 s21, 0
	s_cbranch_vccnz .LBB0_1051
	s_abs_i32 s1, s3
	v_cvt_f32_u32_e32 v1, s1
	s_sub_i32 s2, s3, s33
	s_add_i32 s4, s2, 0x3ff
	s_sub_i32 s2, 0xfffffc01, s2
	v_rcp_iflag_f32_e32 v1, v1
	s_xor_b32 s6, s4, s3
	s_sub_i32 s5, 0, s1
	s_max_i32 s2, s4, s2
	v_mul_f32_e32 v1, 0x4f7ffffe, v1
	v_cvt_u32_f32_e32 v1, v1
	s_ashr_i32 s4, s6, 31
	v_readfirstlane_b32 s6, v1
	s_mul_i32 s5, s5, s6
	s_mul_hi_u32 s5, s6, s5
	s_add_i32 s6, s6, s5
	s_mul_hi_u32 s5, s2, s6
	s_mul_i32 s6, s5, s1
	s_sub_i32 s2, s2, s6
	s_add_i32 s7, s5, 1
	s_sub_i32 s6, s2, s1
	s_cmp_ge_u32 s2, s1
	s_cselect_b32 s5, s7, s5
	s_cselect_b32 s2, s6, s2
	s_add_i32 s6, s5, 1
	s_cmp_ge_u32 s2, s1
	s_cselect_b32 s1, s6, s5
	s_xor_b32 s1, s1, s4
	s_sub_i32 s21, s1, s4
